# combo6 + static s_setprio 1 for waves 4-7 during the attention phase
# baseline (speedup 1.0000x reference)
.LBB0_629:
	v_readfirstlane_b32 s98, v234
	s_lshr_b32 s98, s98, 6
	s_cmp_lt_u32 s98, 4
	s_cbranch_scc1 .Lmy_prio_skip
	s_setprio 1

.LBB0_695:
	s_setprio 0
	s_mov_b64 s[0:1], exec
	v_readlane_b32 s2, v253, 3
	v_readlane_b32 s3, v253, 4
	s_and_b64 s[2:3], s[0:1], s[2:3]
	v_readlane_b32 s60, v253, 55
	v_readlane_b32 s61, v253, 63
	v_readlane_b32 s62, v253, 62
	s_mov_b64 exec, s[2:3]
	s_cbranch_execz .LBB0_705
	s_mov_b32 s2, 0x400001
	v_mov_b32_e32 v0, 0
	s_movk_i32 s3, 0xff
	s_movk_i32 s8, 0x100
	s_branch .LBB0_698
